# S5 table item: all 43 inputs loaded before the x-row loop (retired by that loop's own waits), the item itself is arithmetic and stores only
# baseline (speedup 1.0000x reference)
; __device__ __forceinline__ unsigned pk2(float lo, float hi) { return pg8::cvt_pk_bf16(lo, hi); }
; __device__ __forceinline__ void prologue(const Args& a, LAS unsigned char* lds, int tid, int wave, int lane) {
;     ...
;     float* ss = (float*)(ws + WS_SS); bf16_t* XB = (bf16_t*)(ws + WS_A);
;     for (int m = gw; m < MTOK; m += NGW) {
;         const float* src = (m < NTOK_P) ? a.in[I_XP] + (size_t)m * DM : a.in[I_XS] + (size_t)(m - NTOK_P) * DM;
;         f32x4 v[4]; float s = 0.f;
; #pragma unroll
;         for (int j = 0; j < 4; ++j) { v[j] = __builtin_nontemporal_load((const f32x4*)src + lane + 64 * j); s += (v[j][0] * v[j][0] + v[j][1] * v[j][1]) + (v[j][2] * v[j][2] + v[j][3] * v[j][3]); }
;         s = wave_sum(s);
;     ...
;     for (int i = tid < 16 ? (int)blockIdx.x * 16 + tid : 2 * NG * NP; i < 2 * NG * NP; i += gridDim.x * 16) {
;         const int l = i / (NG * NP), g = (i / NP) % NG, p = i % NP;
;         const float lre = a.in[I_LRE][i], lim = a.in[I_LIM][i], step = expf(a.in[I_LSTEP][l * NG + g]);
;         const float mag = expf(lre * step), ar = mag * cosf(lim * step), ai = mag * sinf(lim * step), den = lre * lre + lim * lim;
;         const float cr = ((ar - 1.f) * lre + ai * lim) / den, ci = (ai * lre - (ar - 1.f) * lim) / den;
;         float pr = ar, pi = ai;
; #pragma unroll
;         for (int k = 0; k < 8; ++k) { const float nr = pr * pr - pi * pi, ni = 2.f * pr * pi; pr = nr; pi = ni; }
;         ((f32x4*)(ws + WS_TA))[i] = (f32x4){ar, ai, pr, pi};
;         bf16_t* tbh = (bf16_t*)(ws + WS_TB) + (size_t)(l * NG + g) * 128 * GC;
;         const float* bre = a.in[I_BRE] + (size_t)i * GC; const float* bim = a.in[I_BIM] + (size_t)i * GC;
; #pragma unroll
;         for (int c = 0; c < GC; c += 2) { const float br0 = bre[c], bi0 = bim[c], br1 = bre[c + 1], bi1 = bim[c + 1];
;             *(unsigned*)(tbh + (2 * p) * GC + c) = pk2(cr * br0 - ci * bi0, cr * br1 - ci * bi1); *(unsigned*)(tbh + (2 * p + 1) * GC + c) = pk2(cr * bi0 + ci * br0, cr * bi1 + ci * br1); }
;         bf16_t* tc = (bf16_t*)(ws + WS_TC) + (size_t)(l * NG + g) * GC * 128;
;         const float* cre = a.in[I_CRE] + (size_t)(l * NG + g) * GC * NP; const float* cim = a.in[I_CIM] + (size_t)(l * NG + g) * GC * NP;
.LBB0_129:
	v_cmp_gt_u32_e32 vcc, 16, v184
	s_and_saveexec_b64 s[98:99], vcc
	s_cbranch_execz .Ltab_early_skip
	v_lshl_add_u32 v136, s2, 4, v184
	v_readlane_b32 s100, v252, 16
	v_readlane_b32 s101, v252, 17
	v_lshlrev_b32_e32 v140, 2, v136
	v_mov_b32_e32 v141, 0
	v_lshrrev_b32_e32 v162, 6, v136
	v_lshlrev_b32_e32 v162, 2, v162
	v_mov_b32_e32 v163, 0
	v_lshl_add_u64 v[138:139], s[84:85], 0, v[162:163]
	global_load_dword v158, v[138:139], off
	v_lshl_add_u64 v[138:139], s[82:83], 0, v[140:141]
	global_load_dword v159, v[138:139], off
	v_lshl_add_u64 v[138:139], s[80:81], 0, v[140:141]
	global_load_dword v160, v[138:139], off
	v_lshlrev_b32_e32 v140, 6, v136
	v_lshl_add_u64 v[138:139], s[100:101], 0, v[140:141]
	v_readlane_b32 s100, v252, 18
	v_readlane_b32 s101, v252, 19
	global_load_dwordx4 v[104:107], v[138:139], off
	global_load_dwordx4 v[108:111], v[138:139], off offset:16
	global_load_dwordx4 v[112:115], v[138:139], off offset:32
	global_load_dwordx4 v[116:119], v[138:139], off offset:48
	v_lshl_add_u64 v[138:139], s[86:87], 0, v[140:141]
	global_load_dwordx4 v[120:123], v[138:139], off
	global_load_dwordx4 v[124:127], v[138:139], off offset:16
	global_load_dwordx4 v[128:131], v[138:139], off offset:32
	global_load_dwordx4 v[132:135], v[138:139], off offset:48
	v_lshlrev_b32_e32 v140, 10, v162
	v_and_b32_e32 v162, 63, v136
	v_lshl_add_u32 v140, v162, 2, v140
	v_lshl_add_u64 v[138:139], s[100:101], 0, v[140:141]
	v_readlane_b32 s100, v252, 20
	v_readlane_b32 s101, v252, 21
	global_load_dword v142, v[138:139], off
	global_load_dword v143, v[138:139], off offset:256
	global_load_dword v144, v[138:139], off offset:512
	global_load_dword v145, v[138:139], off offset:768
	global_load_dword v146, v[138:139], off offset:1024
	global_load_dword v147, v[138:139], off offset:1280
	global_load_dword v148, v[138:139], off offset:1536
	global_load_dword v149, v[138:139], off offset:1792
	global_load_dword v150, v[138:139], off offset:2048
	global_load_dword v151, v[138:139], off offset:2304
	global_load_dword v152, v[138:139], off offset:2560
	global_load_dword v153, v[138:139], off offset:2816
	global_load_dword v154, v[138:139], off offset:3072
	global_load_dword v155, v[138:139], off offset:3328
	global_load_dword v156, v[138:139], off offset:3584
	global_load_dword v157, v[138:139], off offset:3840
	v_lshl_add_u64 v[138:139], s[100:101], 0, v[140:141]
	global_load_dword v64, v[138:139], off
	global_load_dword v65, v[138:139], off offset:256
	global_load_dword v66, v[138:139], off offset:512
	global_load_dword v67, v[138:139], off offset:768
	global_load_dword v68, v[138:139], off offset:1024
	global_load_dword v69, v[138:139], off offset:1280
	global_load_dword v70, v[138:139], off offset:1536
	global_load_dword v71, v[138:139], off offset:1792
	global_load_dword v72, v[138:139], off offset:2048
	global_load_dword v73, v[138:139], off offset:2304
	global_load_dword v74, v[138:139], off offset:2560
	global_load_dword v75, v[138:139], off offset:2816
	global_load_dword v76, v[138:139], off offset:3072
	global_load_dword v77, v[138:139], off offset:3328
	global_load_dword v78, v[138:139], off offset:3584
	global_load_dword v79, v[138:139], off offset:3840
.Ltab_early_skip:
	s_or_b64 exec, exec, s[98:99]
	s_lshl_b32 s62, s2, 3
	s_add_i32 s0, s94, s62
	s_lshl_b32 s66, s34, 3
	s_add_u32 s88, s70, 0x100000
	s_addc_u32 s89, s71, 0
	s_add_u32 s30, s70, 0x3900000
	s_addc_u32 s31, s71, 0
	s_cmpk_gt_i32 s0, 0x41ff
	s_waitcnt vmcnt(5)
	v_mbcnt_lo_u32_b32 v8, -1, 0
	s_cbranch_scc1 .LBB0_136
	v_mbcnt_hi_u32_b32 v0, -1, v8
	v_and_b32_e32 v2, 64, v0
	v_add_u32_e32 v2, 64, v2
	v_xor_b32_e32 v3, 1, v0
	v_cmp_lt_i32_e32 vcc, v3, v2
	s_ashr_i32 s1, s0, 31
	s_ashr_i32 s67, s66, 31
	v_cndmask_b32_e32 v3, v0, v3, vcc
	v_lshlrev_b32_e32 v4, 2, v3
	v_xor_b32_e32 v3, 2, v0
	v_cmp_lt_i32_e32 vcc, v3, v2
	s_lshl_b64 s[6:7], s[0:1], 12
	v_readlane_b32 s8, v252, 0
	v_cndmask_b32_e32 v3, v0, v3, vcc
	v_lshlrev_b32_e32 v5, 2, v3
	v_xor_b32_e32 v3, 4, v0
	v_cmp_lt_i32_e32 vcc, v3, v2
	v_mov_b32_e32 v1, 0
	v_readlane_b32 s9, v252, 1
	v_cndmask_b32_e32 v3, v0, v3, vcc
	v_lshlrev_b32_e32 v6, 2, v3
	v_xor_b32_e32 v3, 8, v0
	v_cmp_lt_i32_e32 vcc, v3, v2
	s_add_u32 s6, s8, s6
	s_mov_b32 s5, 0
	v_cndmask_b32_e32 v3, v0, v3, vcc
	v_lshlrev_b32_e32 v7, 2, v3
	v_xor_b32_e32 v3, 16, v0
	v_cmp_lt_i32_e32 vcc, v3, v2
	s_addc_u32 s7, s9, s7
	s_lshl_b64 s[8:9], s[66:67], 12
	v_cndmask_b32_e32 v3, v0, v3, vcc
	v_lshlrev_b32_e32 v9, 2, v3
	v_xor_b32_e32 v3, 32, v0
	v_cmp_lt_i32_e32 vcc, v3, v2
	v_readlane_b32 s10, v252, 2
	v_readlane_b32 s11, v252, 3
	v_cndmask_b32_e32 v0, v0, v3, vcc
	v_lshlrev_b32_e32 v10, 2, v0
	v_lshlrev_b32_e32 v0, 3, v32
	v_lshl_add_u64 v[2:3], s[30:31], 0, v[0:1]
	v_cmp_eq_u32_e32 vcc, 0, v32
	v_lshlrev_b32_e32 v0, 4, v32
	v_readlane_b32 s12, v252, 4
	v_readlane_b32 s13, v252, 5
	v_readlane_b32 s14, v252, 6
	v_readlane_b32 s15, v252, 7
	v_readlane_b32 s16, v252, 8
	v_readlane_b32 s17, v252, 9
	v_readlane_b32 s18, v252, 10
	v_readlane_b32 s19, v252, 11
	v_readlane_b32 s20, v252, 12
	v_readlane_b32 s21, v252, 13
	v_readlane_b32 s22, v252, 14
	v_readlane_b32 s23, v252, 15
	s_branch .LBB0_132

; __device__ __forceinline__ void prologue(const Args& a, LAS unsigned char* lds, int tid, int wave, int lane) {
;     ...
;         const int l = i / (NG * NP), g = (i / NP) % NG, p = i % NP;
;         const float lre = a.in[I_LRE][i], lim = a.in[I_LIM][i], step = expf(a.in[I_LSTEP][l * NG + g]);
;         const float mag = expf(lre * step), ar = mag * cosf(lim * step), ai = mag * sinf(lim * step), den = lre * lre + lim * lim;
.LBB0_142:
	v_ashrrev_i32_e32 v1, 31, v0
	v_lshrrev_b32_e32 v5, 26, v1
	v_add_u32_e32 v5, v0, v5
	v_ashrrev_i32_e32 v17, 6, v5
	v_lshrrev_b32_e32 v5, 27, v17
	v_lshrrev_b32_e32 v2, 21, v1
	v_add_u32_e32 v5, v17, v5
	v_add_u32_e32 v2, v0, v2
	v_and_b32_e32 v5, 0xffffffe0, v5
	v_ashrrev_i32_e32 v2, 11, v2
	v_sub_u32_e32 v5, v17, v5
	v_lshl_add_u32 v6, v2, 5, v5
	v_ashrrev_i32_e32 v7, 31, v6
	v_lshl_add_u64 v[18:19], v[6:7], 2, s[84:85]
	v_mov_b32_e32 v2, v158
	s_nop 0
	v_lshlrev_b64 v[20:21], 2, v[0:1]
	v_lshl_add_u64 v[18:19], s[82:83], 0, v[20:21]
	v_mov_b32_e32 v18, v159
	v_lshl_add_u64 v[20:21], s[80:81], 0, v[20:21]
	v_mov_b32_e32 v19, v160
	s_nop 0
	v_mul_f32_e32 v5, 0x3fb8aa3b, v2
	v_fma_f32 v20, v2, s24, -v5
	v_rndne_f32_e32 v21, v5
	v_fmac_f32_e32 v20, 0x32a5705f, v2
	v_sub_f32_e32 v5, v5, v21
	v_add_f32_e32 v5, v5, v20
	v_cvt_i32_f32_e32 v21, v21
	v_exp_f32_e32 v5, v5
	v_cmp_ngt_f32_e32 vcc, s25, v2
	v_ldexp_f32 v5, v5, v21
	s_nop 0
	v_cndmask_b32_e32 v5, 0, v5, vcc
	v_cmp_nlt_f32_e32 vcc, s26, v2
	s_nop 1
	v_cndmask_b32_e32 v21, v11, v5, vcc
	s_nop 0
	v_mul_f32_e32 v5, v18, v21
	v_and_b32_e32 v20, 0x7fffffff, v5
	v_lshrrev_b32_e32 v2, 23, v20
	v_and_b32_e32 v22, 0x7fffff, v20
	v_cmp_nlt_f32_e64 s[18:19], |v5|, s27
	v_add_u32_e32 v25, 0xffffff88, v2
	v_or_b32_e32 v24, 0x800000, v22
	s_and_saveexec_b64 s[0:1], s[18:19]
	s_xor_b64 s[20:21], exec, s[0:1]
	s_cbranch_execz .LBB0_144
	v_cmp_lt_u32_e32 vcc, 63, v25
	s_nop 1
	v_cndmask_b32_e32 v2, 0, v14, vcc
	v_add_u32_e32 v2, v2, v25
	v_cmp_lt_u32_e64 s[0:1], 31, v2
	s_nop 1
	v_cndmask_b32_e64 v22, 0, v15, s[0:1]
	v_add_u32_e32 v2, v22, v2
	v_cmp_lt_u32_e64 s[4:5], 31, v2
	s_nop 1
	v_cndmask_b32_e64 v22, 0, v15, s[4:5]
	v_add_u32_e32 v38, v22, v2
	v_mad_u64_u32 v[22:23], s[6:7], v24, s28, 0
	v_mov_b32_e32 v2, v23
	v_mad_u64_u32 v[26:27], s[6:7], v24, s29, v[2:3]
	v_mov_b32_e32 v2, v27
	v_mad_u64_u32 v[28:29], s[6:7], v24, s33, v[2:3]
	v_mov_b32_e32 v2, v29
	v_mad_u64_u32 v[30:31], s[6:7], v24, s54, v[2:3]
	v_mov_b32_e32 v2, v31
	v_mad_u64_u32 v[32:33], s[6:7], v24, s55, v[2:3]
	v_mov_b32_e32 v2, v33
	v_mad_u64_u32 v[34:35], s[6:7], v24, s56, v[2:3]
	v_mov_b32_e32 v2, v35
	v_mad_u64_u32 v[36:37], s[6:7], v24, s57, v[2:3]
	v_cndmask_b32_e32 v23, v34, v30, vcc
	v_cndmask_b32_e32 v2, v36, v32, vcc
	v_cndmask_b32_e32 v29, v37, v34, vcc
	v_cndmask_b32_e64 v27, v2, v23, s[0:1]
	v_cndmask_b32_e64 v2, v29, v2, s[0:1]
	v_cndmask_b32_e32 v29, v32, v28, vcc
	v_cndmask_b32_e64 v23, v23, v29, s[0:1]
	v_cndmask_b32_e32 v26, v30, v26, vcc
	v_cndmask_b32_e64 v2, v2, v27, s[4:5]
	v_cndmask_b32_e64 v27, v27, v23, s[4:5]
	v_sub_u32_e32 v31, 32, v38
	v_cndmask_b32_e64 v29, v29, v26, s[0:1]
	v_alignbit_b32 v32, v2, v27, v31
	v_cmp_eq_u32_e64 s[6:7], 0, v38
	v_cndmask_b32_e64 v23, v23, v29, s[4:5]
	v_cndmask_b32_e32 v22, v28, v22, vcc
	v_cndmask_b32_e64 v2, v32, v2, s[6:7]
	v_alignbit_b32 v30, v27, v23, v31
	v_cndmask_b32_e64 v22, v26, v22, s[0:1]
	v_cndmask_b32_e64 v27, v30, v27, s[6:7]
	v_bfe_u32 v33, v2, 29, 1
	v_cndmask_b32_e64 v22, v29, v22, s[4:5]
	v_alignbit_b32 v30, v2, v27, 30
	v_sub_u32_e32 v34, 0, v33
	v_alignbit_b32 v26, v23, v22, v31
	v_xor_b32_e32 v30, v30, v34
	v_cndmask_b32_e64 v23, v26, v23, s[6:7]
	v_alignbit_b32 v26, v27, v23, 30
	v_ffbh_u32_e32 v27, v30
	v_min_u32_e32 v27, 32, v27
	v_alignbit_b32 v22, v23, v22, 30
	v_xor_b32_e32 v26, v26, v34
	v_sub_u32_e32 v28, 31, v27
	v_xor_b32_e32 v22, v22, v34
	v_alignbit_b32 v29, v30, v26, v28
	v_alignbit_b32 v22, v26, v22, v28
	v_alignbit_b32 v23, v29, v22, 9
	v_ffbh_u32_e32 v26, v23
	v_min_u32_e32 v26, 32, v26
	v_lshrrev_b32_e32 v32, 29, v2
	v_not_b32_e32 v28, v26
	v_alignbit_b32 v22, v23, v22, v28
	v_lshlrev_b32_e32 v23, 31, v32
	v_or_b32_e32 v28, 0x33000000, v23
	v_add_lshl_u32 v26, v26, v27, 23
	v_lshrrev_b32_e32 v22, 9, v22
	v_sub_u32_e32 v26, v28, v26
	v_or_b32_e32 v23, 0.5, v23
	v_lshlrev_b32_e32 v27, 23, v27
	v_or_b32_e32 v22, v26, v22
	v_lshrrev_b32_e32 v26, 9, v29
	v_sub_u32_e32 v23, v23, v27
	v_or_b32_e32 v23, v26, v23
	v_mul_f32_e32 v26, 0x3fc90fda, v23
	v_fma_f32 v27, v23, s60, -v26
	v_fmac_f32_e32 v27, 0x33a22168, v23
	v_fmac_f32_e32 v27, 0x3fc90fda, v22
	v_lshrrev_b32_e32 v2, 30, v2
	v_add_f32_e32 v23, v26, v27
	v_add_u32_e32 v22, v33, v2
